# pair8d plus one s_barrier per x-packer block so that the two waves that write a shared XB8 line store at the same time
# speedup vs baseline: 1.0050x; 1.0050x over previous
; #define LAS __attribute__((address_space(3)))
; #define LDS_WAIT() asm volatile("s_waitcnt lgkmcnt(0)" ::: "memory")
; __device__ __forceinline__ unsigned pk2(float lo, float hi) { return cvt_pk_bf16(lo, hi); }
;     __device__ __forceinline__ unsigned a(const pg8::Unit& u) const { return (unsigned)u.pm * (256u * K * 2u); }
;     __device__ __forceinline__ unsigned a(const pg8::Unit& u) const { return (unsigned)u.pm * (256u * K * 2u); }
;     __device__ __forceinline__ unsigned a(const pg8::Unit& u) const { return (unsigned)u.pm * (256u * K * 2u); }
;     __device__ __forceinline__ unsigned a(const pg8::Unit& u) const { return (unsigned)u.pm * (256u * K * 2u); }
;     __device__ __forceinline__ unsigned a(const pg8::Unit& u) const { return (unsigned)u.pm * (256u * K * 2u); }
; __device__ __forceinline__ void p0_prologue(const Frame& F) {
;     ...
; #pragma unroll
;             for (int i = 0; i < 4; ++i) {
;                 const int p8 = i * 64 + plane; const size_t e = e0 + (size_t)p8 * 8;
;                 u32x4 w; w.x = pk2(a[i][0], a[i][1]); w.y = pk2(a[i][2], a[i][3]); w.z = pk2(b[i][0], b[i][1]); w.w = pk2(b[i][2], b[i][3]);
;                 *(u32x4*)(F.XB + e) = w;
;                 const float xv[8] = {a[i][0], a[i][1], a[i][2], a[i][3], b[i][0], b[i][1], b[i][2], b[i][3]};
;                 *(unsigned*)(F.XB4 + e / 2) = q4x8(xv, X4_SCALE);
;                 LAS float* d = scr + (p8 >> 2) * 36 + (p8 & 3) * 8;
;                 *(LAS f32x4*)d = a[i]; *(LAS f32x4*)(d + 4) = b[i];
;             }
;             LDS_WAIT(); asm volatile("" ::: "memory");
.LBB0_51:
	v_cvt_pk_bf16_f32 v86, v28, v29
	v_cvt_pk_bf16_f32 v87, v30, v31
	v_cvt_pk_bf16_f32 v88, v24, v25
	v_cvt_pk_bf16_f32 v89, v26, v27
	v_add_f32_e32 v33, v28, v28
	v_add_f32_e32 v69, v29, v29
	global_store_dwordx4 v[72:73], v[86:89], off offset:-2048
	v_med3_f32 v33, v33, s35, v84
	v_med3_f32 v69, v69, s35, v84
	v_mov_b32_e32 v88, 0
	v_cvt_scalef32_pk_fp4_f32 v88, v33, v69, 1.0
	v_add_f32_e32 v33, v30, v30
	v_add_f32_e32 v69, v31, v31
	v_med3_f32 v33, v33, s35, v84
	v_med3_f32 v69, v69, s35, v84
	v_cvt_scalef32_pk_fp4_f32 v88, v33, v69, 1.0 op_sel:[0,0,1,0]
	v_add_f32_e32 v33, v24, v24
	v_add_f32_e32 v69, v25, v25
	v_med3_f32 v33, v33, s35, v84
	v_med3_f32 v69, v69, s35, v84
	v_lshl_add_u64 v[90:91], s[4:5], 0, v[78:79]
	v_cvt_scalef32_pk_fp4_f32 v88, v33, v69, 1.0 op_sel:[0,0,0,1]
	v_add_f32_e32 v33, v26, v26
	v_add_f32_e32 v69, v27, v27
	v_med3_f32 v33, v33, s35, v84
	v_med3_f32 v69, v69, s35, v84
	v_lshrrev_b64 v[86:87], 1, v[90:91]
	v_cvt_scalef32_pk_fp4_f32 v88, v33, v69, 1.0 op_sel:[0,0,1,1]
	v_lshl_add_u64 v[86:87], s[52:53], 0, v[86:87]
	global_store_dword v[86:87], v88, off
	ds_write_b128 v67, v[28:31]
	ds_write_b128 v67, v[24:27] offset:16
	v_cvt_pk_bf16_f32 v24, v20, v21
	v_cvt_pk_bf16_f32 v25, v22, v23
	v_cvt_pk_bf16_f32 v26, v16, v17
	v_cvt_pk_bf16_f32 v27, v18, v19
	global_store_dwordx4 v[72:73], v[24:27], off offset:-1024
	v_lshl_add_u64 v[28:29], v[90:91], 0, s[68:69]
	v_lshl_add_u64 v[86:87], v[70:71], 0, s[4:5]
	v_add_f32_e32 v24, v20, v20
	v_add_f32_e32 v25, v21, v21
	v_med3_f32 v24, v24, s35, v84
	v_med3_f32 v25, v25, s35, v84
	v_mov_b32_e32 v26, 0
	v_cvt_scalef32_pk_fp4_f32 v26, v24, v25, 1.0
	v_add_f32_e32 v24, v22, v22
	v_add_f32_e32 v25, v23, v23
	v_med3_f32 v24, v24, s35, v84
	v_med3_f32 v25, v25, s35, v84
	v_cvt_scalef32_pk_fp4_f32 v26, v24, v25, 1.0 op_sel:[0,0,1,0]
	v_add_f32_e32 v24, v16, v16
	v_add_f32_e32 v25, v17, v17
	v_med3_f32 v24, v24, s35, v84
	v_med3_f32 v25, v25, s35, v84
	v_cvt_scalef32_pk_fp4_f32 v26, v24, v25, 1.0 op_sel:[0,0,0,1]
	v_add_f32_e32 v24, v18, v18
	v_add_f32_e32 v25, v19, v19
	v_med3_f32 v24, v24, s35, v84
	v_med3_f32 v25, v25, s35, v84
	v_cvt_scalef32_pk_fp4_f32 v26, v24, v25, 1.0 op_sel:[0,0,1,1]
	v_lshrrev_b64 v[24:25], 1, v[28:29]
	v_lshl_add_u64 v[24:25], s[52:53], 0, v[24:25]
	global_store_dword v[24:25], v26, off
	ds_write_b128 v80, v[20:23]
	ds_write_b128 v80, v[16:19] offset:16
	v_cvt_pk_bf16_f32 v16, v12, v13
	v_cvt_pk_bf16_f32 v17, v14, v15
	v_cvt_pk_bf16_f32 v18, v8, v9
	v_cvt_pk_bf16_f32 v19, v10, v11
	global_store_dwordx4 v[72:73], v[16:19], off
	v_lshl_add_u64 v[20:21], v[90:91], 0, s[70:71]
	v_mov_b32_e32 v33, v32
	v_add_f32_e32 v16, v12, v12
	v_add_f32_e32 v17, v13, v13
	v_med3_f32 v16, v16, s35, v84
	v_med3_f32 v17, v17, s35, v84
	v_mov_b32_e32 v18, 0
	v_cvt_scalef32_pk_fp4_f32 v18, v16, v17, 1.0
	v_add_f32_e32 v16, v14, v14
	v_add_f32_e32 v17, v15, v15
	v_med3_f32 v16, v16, s35, v84
	v_med3_f32 v17, v17, s35, v84
	v_cvt_scalef32_pk_fp4_f32 v18, v16, v17, 1.0 op_sel:[0,0,1,0]
	v_add_f32_e32 v16, v8, v8
	v_add_f32_e32 v17, v9, v9
	v_med3_f32 v16, v16, s35, v84
	v_med3_f32 v17, v17, s35, v84
	v_cvt_scalef32_pk_fp4_f32 v18, v16, v17, 1.0 op_sel:[0,0,0,1]
	v_add_f32_e32 v16, v10, v10
	v_add_f32_e32 v17, v11, v11
	v_med3_f32 v16, v16, s35, v84
	v_med3_f32 v17, v17, s35, v84
	v_cvt_scalef32_pk_fp4_f32 v18, v16, v17, 1.0 op_sel:[0,0,1,1]
	v_lshrrev_b64 v[16:17], 1, v[20:21]
	v_lshl_add_u64 v[16:17], s[52:53], 0, v[16:17]
	global_store_dword v[16:17], v18, off
	ds_write_b128 v81, v[12:15]
	ds_write_b128 v81, v[8:11] offset:16
	v_cvt_pk_bf16_f32 v8, v4, v5
	v_cvt_pk_bf16_f32 v9, v6, v7
	v_cvt_pk_bf16_f32 v10, v0, v1
	v_cvt_pk_bf16_f32 v11, v2, v3
	global_store_dwordx4 v[72:73], v[8:11], off offset:1024
	v_lshl_add_u64 v[12:13], v[90:91], 0, s[76:77]
	s_add_u32 s16, s16, s58
	v_add_f32_e32 v8, v4, v4
	v_add_f32_e32 v9, v5, v5
	v_med3_f32 v8, v8, s35, v84
	v_med3_f32 v9, v9, s35, v84
	v_mov_b32_e32 v10, 0
	v_cvt_scalef32_pk_fp4_f32 v10, v8, v9, 1.0
	v_add_f32_e32 v8, v6, v6
	v_add_f32_e32 v9, v7, v7
	v_med3_f32 v8, v8, s35, v84
	v_med3_f32 v9, v9, s35, v84
	v_cvt_scalef32_pk_fp4_f32 v10, v8, v9, 1.0 op_sel:[0,0,1,0]
	v_add_f32_e32 v8, v0, v0
	v_add_f32_e32 v9, v1, v1
	v_med3_f32 v8, v8, s35, v84
	v_med3_f32 v9, v9, s35, v84
	v_cvt_scalef32_pk_fp4_f32 v10, v8, v9, 1.0 op_sel:[0,0,0,1]
	v_add_f32_e32 v8, v2, v2
	v_add_f32_e32 v9, v3, v3
	v_med3_f32 v8, v8, s35, v84
	v_med3_f32 v9, v9, s35, v84
	v_cvt_scalef32_pk_fp4_f32 v10, v8, v9, 1.0 op_sel:[0,0,1,1]
	v_lshrrev_b64 v[8:9], 1, v[12:13]
	v_lshl_add_u64 v[8:9], s[52:53], 0, v[8:9]
	global_store_dword v[8:9], v10, off
	ds_write_b128 v82, v[4:7]
	ds_write_b128 v82, v[0:3] offset:16
	s_waitcnt lgkmcnt(0)
; #define LAS __attribute__((address_space(3)))
; #define LDS_WAIT() asm volatile("s_waitcnt lgkmcnt(0)" ::: "memory")
; __device__ __forceinline__ void p0_prologue(const Frame& F) {
;     ...
;             float v[32];
; #pragma unroll
;             for (int j = 0; j < 8; ++j) { const f32x4 t = *(const LAS f32x4*)(scr + plane * 36 + j * 4); v[4 * j] = t[0]; v[4 * j + 1] = t[1]; v[4 * j + 2] = t[2]; v[4 * j + 3] = t[3]; }
;             const size_t eg = e0 + (size_t)plane * 32;
;             store_fp6_group(F.XB8 + (eg >> 7) * 128 + ((eg >> 5) & 3) * 16, v, X6_SCALE);
;             LDS_WAIT(); asm volatile("" ::: "memory");
	ds_read_b128 v[0:3], v83
	ds_read_b128 v[4:7], v83 offset:16
	ds_read_b128 v[8:11], v83 offset:32
	ds_read_b128 v[12:15], v83 offset:48
	ds_read_b128 v[16:19], v83 offset:64
	ds_read_b128 v[20:23], v83 offset:80
	ds_read_b128 v[24:27], v83 offset:96
	ds_read_b128 v[28:31], v83 offset:112
	s_waitcnt lgkmcnt(7)
	v_add_f32_e32 v0, v0, v0
	s_waitcnt lgkmcnt(3)
	v_add_f32_e32 v16, v16, v16
	v_add_f32_e32 v1, v1, v1
	v_add_f32_e32 v17, v17, v17
	v_add_f32_e32 v2, v2, v2
	v_add_f32_e32 v18, v18, v18
	v_add_f32_e32 v3, v3, v3
	v_add_f32_e32 v19, v19, v19
	v_add_f32_e32 v4, v4, v4
	s_waitcnt lgkmcnt(2)
	v_add_f32_e32 v20, v20, v20
	v_add_f32_e32 v5, v5, v5
	v_add_f32_e32 v21, v21, v21
	v_add_f32_e32 v6, v6, v6
	v_add_f32_e32 v22, v22, v22
	v_add_f32_e32 v7, v7, v7
	v_add_f32_e32 v23, v23, v23
	v_add_f32_e32 v8, v8, v8
	s_waitcnt lgkmcnt(1)
	v_add_f32_e32 v24, v24, v24
	v_add_f32_e32 v9, v9, v9
	v_add_f32_e32 v25, v25, v25
	v_add_f32_e32 v10, v10, v10
	v_add_f32_e32 v26, v26, v26
	v_add_f32_e32 v11, v11, v11
	v_add_f32_e32 v27, v27, v27
	v_add_f32_e32 v12, v12, v12
	s_waitcnt lgkmcnt(0)
	v_add_f32_e32 v28, v28, v28
	v_add_f32_e32 v13, v13, v13
	v_add_f32_e32 v29, v29, v29
	v_add_f32_e32 v14, v14, v14
	v_add_f32_e32 v30, v30, v30
	v_add_f32_e32 v15, v15, v15
	v_add_f32_e32 v31, v31, v31
	v_med3_f32 v0, v0, s3, v85
	v_med3_f32 v16, v16, s3, v85
	v_med3_f32 v1, v1, s3, v85
	v_med3_f32 v17, v17, s3, v85
	v_med3_f32 v2, v2, s3, v85
	v_med3_f32 v18, v18, s3, v85
	v_med3_f32 v3, v3, s3, v85
	v_med3_f32 v19, v19, s3, v85
	v_med3_f32 v4, v4, s3, v85
	v_med3_f32 v20, v20, s3, v85
	v_med3_f32 v5, v5, s3, v85
	v_med3_f32 v21, v21, s3, v85
	v_med3_f32 v6, v6, s3, v85
	v_med3_f32 v22, v22, s3, v85
	v_med3_f32 v7, v7, s3, v85
	v_med3_f32 v23, v23, s3, v85
	v_med3_f32 v8, v8, s3, v85
	v_med3_f32 v24, v24, s3, v85
	v_med3_f32 v9, v9, s3, v85
	v_med3_f32 v25, v25, s3, v85
	v_med3_f32 v10, v10, s3, v85
	v_med3_f32 v26, v26, s3, v85
	v_med3_f32 v11, v11, s3, v85
	v_med3_f32 v27, v27, s3, v85
	v_med3_f32 v12, v12, s3, v85
	v_med3_f32 v28, v28, s3, v85
	v_med3_f32 v13, v13, s3, v85
	v_med3_f32 v29, v29, s3, v85
	v_med3_f32 v14, v14, s3, v85
	v_med3_f32 v30, v30, s3, v85
	v_med3_f32 v15, v15, s3, v85
	v_med3_f32 v31, v31, s3, v85
	v_cvt_scalef32_2xpk16_fp6_f32 v[0:5], v[0:15], v[16:31], 1.0
	v_add_co_u32_e32 v6, vcc, s72, v86
	v_mov_b32_e32 v30, v4
	s_nop 0
	v_addc_co_u32_e32 v7, vcc, 0, v87, vcc
	v_mov_b32_e32 v31, v5
	v_mbcnt_lo_u32_b32 v8, -1, 0
	v_mbcnt_hi_u32_b32 v8, -1, v8
	v_and_b32_e32 v8, 3, v8
	v_mov_b32_e32 v9, s50
	v_bfe_u32 v15, v9, 4, 1
	v_bfe_u32 v14, v9, 7, 1
	v_bfe_u32 v12, v9, 1, 1
	v_and_b32_e32 v12, v12, v14
	v_mul_u32_u24_e32 v12, 0xfc0, v12
	v_bfe_u32 v9, v9, 3, 2
	v_and_b32_e32 v13, 1, v9
	v_sub_u32_e32 v9, 0, v9
	v_and_b32_e32 v9, 3, v9
	v_xor_b32_e32 v9, v8, v9
	v_sub_u32_e32 v9, v9, v8
	v_lshlrev_b32_e32 v10, 4, v9
	v_sub_u32_e32 v10, v10, v12
	v_ashrrev_i32_e32 v11, 31, v10
	v_lshl_add_u64 v[10:11], v[6:7], 0, v[10:11]
	s_barrier
	global_store_dwordx4 v[10:11], v[0:3], off
	v_xor_b32_e32 v13, v14, v13
	v_lshlrev_b32_e32 v13, 5, v13
	v_lshlrev_b32_e32 v14, 18, v14
	v_sub_u32_e32 v13, v13, v14
	v_lshrrev_b32_e32 v14, 1, v8
	v_xor_b32_e32 v14, v14, v15
	v_lshl_add_u32 v13, v14, 4, v13
	v_and_b32_e32 v14, 1, v8
	v_lshl_add_u32 v13, v14, 3, v13
	v_lshlrev_b32_e32 v14, 4, v8
	v_sub_u32_e32 v12, v13, v14
	v_ashrrev_i32_e32 v13, 31, v12
	v_lshl_add_u64 v[12:13], v[6:7], 0, v[12:13]
	global_store_dwordx2 v[12:13], v[30:31], off offset:64
	s_waitcnt lgkmcnt(0)
	s_waitcnt vmcnt(17)
	v_mov_b64_e32 v[24:25], v[34:35]
	s_waitcnt vmcnt(15)
	v_mov_b64_e32 v[16:17], v[42:43]
	s_waitcnt vmcnt(12)
	v_mov_b64_e32 v[8:9], v[50:51]
	s_waitcnt vmcnt(10)
	v_mov_b64_e32 v[0:1], v[58:59]
	v_mov_b64_e32 v[28:29], v[38:39]
	v_mov_b64_e32 v[20:21], v[46:47]
	v_mov_b64_e32 v[12:13], v[54:55]
	v_mov_b64_e32 v[4:5], v[62:63]
	s_addc_u32 s17, s17, s59
	v_lshl_add_u64 v[70:71], v[70:71], 0, s[62:63]
	v_lshl_add_u64 v[78:79], v[78:79], 0, s[62:63]
	v_lshl_add_u64 v[72:73], v[72:73], 0, s[66:67]
	s_andn2_b64 vcc, exec, s[0:1]
	v_mov_b64_e32 v[26:27], v[36:37]
	v_mov_b64_e32 v[18:19], v[44:45]
	v_mov_b64_e32 v[10:11], v[52:53]
	v_mov_b64_e32 v[2:3], v[60:61]
	v_mov_b64_e32 v[30:31], v[40:41]
	v_mov_b64_e32 v[22:23], v[48:49]
	v_mov_b64_e32 v[14:15], v[56:57]
	v_mov_b64_e32 v[6:7], v[64:65]
	s_cbranch_vccz .LBB0_54
